# early-L1-invalidate-in-shared-barrier
# speedup vs baseline: 1.0997x; 1.0997x over previous
.Lsbar:
	v_readlane_b32 s99, v242, 11
	v_readlane_b32 s100, v242, 30
	s_add_u32 s101, s98, 1
	s_nop 0
	v_mov_b32_e32 v244, s99
	ds_read_b32 v245, v244
	ds_read_b32 v246, v244 offset:4
	s_lshl_b32 s100, s100, 8
	s_add_u32 s100, s100, 0x1400
	v_mov_b32_e32 v247, s100
	v_mov_b32_e32 v248, 1
	global_atomic_add v249, v247, v248, s[70:71] sc0
	buffer_inv sc1
	s_waitcnt lgkmcnt(0)
	v_mul_lo_u32 v245, v245, s101
	v_mul_lo_u32 v246, v246, s101
	v_mov_b32_e32 v250, 0x3500
	v_mov_b32_e32 v251, s98
	s_mov_b32 s99, 0
	s_waitcnt vmcnt(0)
	v_add_u32_e32 v249, 1, v249
	v_cmp_eq_u32_e32 vcc, v249, v245
	s_cbranch_vccz .Lsbar_poll
	buffer_wbl2 sc1
	s_waitcnt vmcnt(0)
	v_mov_b32_e32 v247, 0x3400
	global_atomic_add v249, v247, v248, s[70:71] sc0
	s_waitcnt vmcnt(0)
	v_add_u32_e32 v249, 1, v249
	v_cmp_eq_u32_e32 vcc, v249, v246
	s_cbranch_vccz .Lsbar_poll
	global_atomic_add v250, v248, s[70:71]
	s_branch .Lsbar_acq
